# attention softmax section rewritten lean: scalar f32 adds instead of SLP v_pk_add/v_pk_mov, in-place exps, no s_nop between v_max3 (on v18)
# speedup vs baseline: 1.0101x; 1.0101x over previous
; __device__ __forceinline__ void att_qk_sm(const LAS unsigned char* kb, int klane, const bf16x8 (&qf)[12], f32x16 (&o)[4], float& mrun, float& lrun, bf16x8 (&pb)[4]) {
;     ...
;     float mx = fmaxf(s0[0], s1[0]);
; #pragma unroll
;     for (int i = 1; i < 16; ++i) asm("v_max3_f32 %0, %1, %2, %3" : "=v"(mx) : "v"(mx), "v"(s0[i]), "v"(s1[i]));
;     { const auto rr = __builtin_amdgcn_permlane32_swap(__float_as_uint(mx), __float_as_uint(mx), false, false);
;       mx = fmaxf(__uint_as_float(rr[0]), __uint_as_float(rr[1])); }
;     if (!__all(mx - mrun <= 8.0f)) {
;         const float mn = fmaxf(mrun, mx), al = __builtin_amdgcn_exp2f(mrun - mn);
;         mrun = mn; lrun *= al;
; #pragma unroll
;         for (int d = 0; d < 4; ++d) o[d] = o[d] * al;
;     }
;     float ps = 0.f;
; #pragma unroll
;     for (int i = 0; i < 16; ++i) { s0[i] = __builtin_amdgcn_exp2f(s0[i] - mrun); s1[i] = __builtin_amdgcn_exp2f(s1[i] - mrun); ps += s0[i] + s1[i]; }
;     lrun += ps;
;     pb[0] = pack8bf(s0[0], s0[1], s0[2], s0[3], s0[4], s0[5], s0[6], s0[7]);
;     pb[1] = pack8bf(s0[8], s0[9], s0[10], s0[11], s0[12], s0[13], s0[14], s0[15]);
;     pb[2] = pack8bf(s1[0], s1[1], s1[2], s1[3], s1[4], s1[5], s1[6], s1[7]);
;     pb[3] = pack8bf(s1[8], s1[9], s1[10], s1[11], s1[12], s1[13], s1[14], s1[15]);
.Latt_issued_q:
	v_max_f32_e32 v170, v64, v80
	v_max3_f32 v170, v170, v81, v65
	v_max3_f32 v170, v170, v82, v66
	v_max3_f32 v170, v170, v83, v67
	v_max3_f32 v170, v170, v84, v68
	v_max3_f32 v170, v170, v85, v69
	v_max3_f32 v170, v170, v86, v70
	v_max3_f32 v170, v170, v87, v71
	v_max3_f32 v170, v170, v88, v72
	v_max3_f32 v170, v170, v89, v73
	v_max3_f32 v170, v170, v90, v74
	v_max3_f32 v170, v170, v91, v75
	v_max3_f32 v170, v170, v92, v76
	v_max3_f32 v170, v170, v93, v77
	v_max3_f32 v170, v170, v94, v78
	v_max3_f32 v170, v170, v95, v79
	v_mov_b32_e32 v171, v170
	s_nop 1
	v_permlane32_swap_b32_e32 v170, v171
	v_max_f32_e32 v170, v170, v171
	v_sub_f32_e32 v171, v170, v169
	v_cmp_ge_f32_e32 vcc, s37, v171
	s_cmp_eq_u64 vcc, exec
	s_cbranch_scc1 .LBB0_1021
	v_max_f32_e32 v170, v170, v170
	v_max_f32_e32 v171, v169, v169
	v_max_f32_e32 v171, v171, v170
	v_sub_f32_e32 v169, v169, v171
	v_exp_f32_e32 v170, v169
	v_mov_b32_e32 v169, v171
	v_mul_f32_e32 v168, v168, v170
	v_pk_mul_f32 v[62:63], v[62:63], v[170:171] op_sel_hi:[1,0]
	v_pk_mul_f32 v[60:61], v[60:61], v[170:171] op_sel_hi:[1,0]
	v_pk_mul_f32 v[58:59], v[58:59], v[170:171] op_sel_hi:[1,0]
	v_pk_mul_f32 v[56:57], v[56:57], v[170:171] op_sel_hi:[1,0]
	v_pk_mul_f32 v[54:55], v[54:55], v[170:171] op_sel_hi:[1,0]
	v_pk_mul_f32 v[52:53], v[52:53], v[170:171] op_sel_hi:[1,0]
	v_pk_mul_f32 v[50:51], v[50:51], v[170:171] op_sel_hi:[1,0]
	v_pk_mul_f32 v[48:49], v[48:49], v[170:171] op_sel_hi:[1,0]
	v_pk_mul_f32 v[46:47], v[46:47], v[170:171] op_sel_hi:[1,0]
	v_pk_mul_f32 v[44:45], v[44:45], v[170:171] op_sel_hi:[1,0]
	v_pk_mul_f32 v[42:43], v[42:43], v[170:171] op_sel_hi:[1,0]
	v_pk_mul_f32 v[40:41], v[40:41], v[170:171] op_sel_hi:[1,0]
	v_pk_mul_f32 v[38:39], v[38:39], v[170:171] op_sel_hi:[1,0]
	v_pk_mul_f32 v[36:37], v[36:37], v[170:171] op_sel_hi:[1,0]
	v_pk_mul_f32 v[34:35], v[34:35], v[170:171] op_sel_hi:[1,0]
	v_pk_mul_f32 v[32:33], v[32:33], v[170:171] op_sel_hi:[1,0]
	v_pk_mul_f32 v[30:31], v[30:31], v[170:171] op_sel_hi:[1,0]
	v_pk_mul_f32 v[28:29], v[28:29], v[170:171] op_sel_hi:[1,0]
	v_pk_mul_f32 v[26:27], v[26:27], v[170:171] op_sel_hi:[1,0]
	v_pk_mul_f32 v[24:25], v[24:25], v[170:171] op_sel_hi:[1,0]
	v_pk_mul_f32 v[22:23], v[22:23], v[170:171] op_sel_hi:[1,0]
	v_pk_mul_f32 v[20:21], v[20:21], v[170:171] op_sel_hi:[1,0]
	v_pk_mul_f32 v[18:19], v[18:19], v[170:171] op_sel_hi:[1,0]
	v_pk_mul_f32 v[16:17], v[16:17], v[170:171] op_sel_hi:[1,0]
	v_pk_mul_f32 v[14:15], v[14:15], v[170:171] op_sel_hi:[1,0]
	v_pk_mul_f32 v[12:13], v[12:13], v[170:171] op_sel_hi:[1,0]
	v_pk_mul_f32 v[10:11], v[10:11], v[170:171] op_sel_hi:[1,0]
	v_pk_mul_f32 v[8:9], v[8:9], v[170:171] op_sel_hi:[1,0]
	v_pk_mul_f32 v[6:7], v[6:7], v[170:171] op_sel_hi:[1,0]
	v_pk_mul_f32 v[4:5], v[4:5], v[170:171] op_sel_hi:[1,0]
	v_pk_mul_f32 v[2:3], v[2:3], v[170:171] op_sel_hi:[1,0]
	v_pk_mul_f32 v[0:1], v[0:1], v[170:171] op_sel_hi:[1,0]
.LBB0_1021:
	v_sub_f32_e32 v80, v80, v169
	v_sub_f32_e32 v64, v64, v169
	v_sub_f32_e32 v81, v81, v169
	v_sub_f32_e32 v65, v65, v169
	v_sub_f32_e32 v82, v82, v169
	v_sub_f32_e32 v66, v66, v169
	v_sub_f32_e32 v83, v83, v169
	v_sub_f32_e32 v67, v67, v169
	v_sub_f32_e32 v84, v84, v169
	v_sub_f32_e32 v68, v68, v169
	v_sub_f32_e32 v85, v85, v169
	v_sub_f32_e32 v69, v69, v169
	v_sub_f32_e32 v86, v86, v169
	v_sub_f32_e32 v70, v70, v169
	v_sub_f32_e32 v87, v87, v169
	v_sub_f32_e32 v71, v71, v169
	v_sub_f32_e32 v88, v88, v169
	v_sub_f32_e32 v72, v72, v169
	v_sub_f32_e32 v89, v89, v169
	v_sub_f32_e32 v73, v73, v169
	v_sub_f32_e32 v90, v90, v169
	v_sub_f32_e32 v74, v74, v169
	v_sub_f32_e32 v91, v91, v169
	v_sub_f32_e32 v75, v75, v169
	v_sub_f32_e32 v92, v92, v169
	v_sub_f32_e32 v76, v76, v169
	v_sub_f32_e32 v93, v93, v169
	v_sub_f32_e32 v77, v77, v169
	v_sub_f32_e32 v94, v94, v169
	v_sub_f32_e32 v78, v78, v169
	v_sub_f32_e32 v95, v95, v169
	v_sub_f32_e32 v79, v79, v169
	v_exp_f32_e32 v80, v80
	v_exp_f32_e32 v64, v64
	v_exp_f32_e32 v81, v81
	v_exp_f32_e32 v65, v65
	v_exp_f32_e32 v82, v82
	v_exp_f32_e32 v66, v66
	v_exp_f32_e32 v83, v83
	v_exp_f32_e32 v67, v67
	v_exp_f32_e32 v84, v84
	v_exp_f32_e32 v68, v68
	v_exp_f32_e32 v85, v85
	v_exp_f32_e32 v69, v69
	v_exp_f32_e32 v86, v86
	v_exp_f32_e32 v70, v70
	v_exp_f32_e32 v87, v87
	v_exp_f32_e32 v71, v71
	v_exp_f32_e32 v88, v88
	v_exp_f32_e32 v72, v72
	v_exp_f32_e32 v89, v89
	v_exp_f32_e32 v73, v73
	v_exp_f32_e32 v90, v90
	v_exp_f32_e32 v74, v74
	v_exp_f32_e32 v91, v91
	v_exp_f32_e32 v75, v75
	v_exp_f32_e32 v92, v92
	v_exp_f32_e32 v76, v76
	v_exp_f32_e32 v93, v93
	v_exp_f32_e32 v77, v77
	v_exp_f32_e32 v94, v94
	v_exp_f32_e32 v78, v78
	v_exp_f32_e32 v95, v95
	v_exp_f32_e32 v79, v79
	v_add_f32_e32 v170, v80, v81
	v_add_f32_e32 v171, v82, v83
	v_add_f32_e32 v170, v170, v84
	v_add_f32_e32 v171, v171, v85
	v_add_f32_e32 v170, v170, v86
	v_add_f32_e32 v171, v171, v87
	v_add_f32_e32 v170, v170, v88
	v_add_f32_e32 v171, v171, v89
	v_add_f32_e32 v170, v170, v90
	v_add_f32_e32 v171, v171, v91
	v_add_f32_e32 v170, v170, v92
	v_add_f32_e32 v171, v171, v93
	v_add_f32_e32 v170, v170, v94
	v_add_f32_e32 v171, v171, v95
	v_add_f32_e32 v170, v170, v64
	v_add_f32_e32 v171, v171, v65
	v_add_f32_e32 v170, v170, v66
	v_add_f32_e32 v171, v171, v67
	v_add_f32_e32 v170, v170, v68
	v_add_f32_e32 v171, v171, v69
	v_add_f32_e32 v170, v170, v70
	v_add_f32_e32 v171, v171, v71
	v_add_f32_e32 v170, v170, v72
	v_add_f32_e32 v171, v171, v73
	v_add_f32_e32 v170, v170, v74
	v_add_f32_e32 v171, v171, v75
	v_add_f32_e32 v170, v170, v76
	v_add_f32_e32 v171, v171, v77
	v_add_f32_e32 v170, v170, v78
	v_add_f32_e32 v171, v171, v79
	v_add_f32_e32 v170, v170, v171
	v_cvt_pk_bf16_f32 v71, v70, v71
	v_cvt_pk_bf16_f32 v70, v68, v69
	v_cvt_pk_bf16_f32 v69, v66, v67
	v_cvt_pk_bf16_f32 v68, v64, v65
	v_add_f32_e32 v168, v168, v170
	v_cvt_pk_bf16_f32 v64, v72, v73
	v_cvt_pk_bf16_f32 v65, v74, v75
	v_cvt_pk_bf16_f32 v66, v76, v77
	v_cvt_pk_bf16_f32 v67, v78, v79
	v_cvt_pk_bf16_f32 v72, v88, v89
	v_cvt_pk_bf16_f32 v73, v90, v91
	v_cvt_pk_bf16_f32 v74, v92, v93
	v_cvt_pk_bf16_f32 v75, v94, v95
	v_cvt_pk_bf16_f32 v76, v80, v81
	v_cvt_pk_bf16_f32 v77, v82, v83
	v_cvt_pk_bf16_f32 v78, v84, v85
	v_cvt_pk_bf16_f32 v79, v86, v87
